# GLA state-update block: decay/ke^T fragment reads pipelined 4 k-blocks deep with counted waits
# baseline (speedup 1.0000x reference)
.LBB0_3088:
	v_add_u32_e32 v115, 0x12000, v196
	s_add_i32 s93, s93, 1
	s_add_i32 s92, s92, 64
	s_sub_i32 s75, s75, 64
	ds_read_b128 v[84:87], v115
	ds_read_b128 v[88:91], v208 offset:34816
	ds_read_b128 v[92:95], v208 offset:34880
	ds_read_b128 v[162:165], v115 offset:64
	ds_read_b128 v[166:169], v208 offset:37120
	ds_read_b128 v[170:173], v208 offset:37184
	ds_read_b128 v[216:219], v115 offset:128
	ds_read_b128 v[220:223], v208 offset:39424
	ds_read_b128 v[224:227], v208 offset:39488
	ds_read_b128 v[228:231], v115 offset:192
	ds_read_b128 v[232:235], v208 offset:41728
	ds_read_b128 v[236:239], v208 offset:41792
	s_waitcnt lgkmcnt(9)
	v_pk_mul_f32 v[44:45], v[44:45], v[84:85]
	v_pk_mul_f32 v[46:47], v[46:47], v[86:87]
	s_nop 1
	v_mfma_f32_16x16x32_bf16 v[44:47], v[88:91], v[80:83], v[44:47]
	v_mfma_f32_16x16x32_bf16 v[44:47], v[92:95], v[76:79], v[44:47]
	ds_read_b128 v[84:87], v115 offset:256
	ds_read_b128 v[88:91], v208 offset:44032
	ds_read_b128 v[92:95], v208 offset:44096
	s_waitcnt lgkmcnt(9)
	v_pk_mul_f32 v[52:53], v[52:53], v[162:163]
	v_pk_mul_f32 v[54:55], v[54:55], v[164:165]
	s_nop 1
	v_mfma_f32_16x16x32_bf16 v[52:55], v[166:169], v[80:83], v[52:55]
	v_mfma_f32_16x16x32_bf16 v[52:55], v[170:173], v[76:79], v[52:55]
	ds_read_b128 v[162:165], v115 offset:320
	ds_read_b128 v[166:169], v208 offset:46336
	ds_read_b128 v[170:173], v208 offset:46400
	s_waitcnt lgkmcnt(9)
	v_pk_mul_f32 v[48:49], v[48:49], v[216:217]
	v_pk_mul_f32 v[50:51], v[50:51], v[218:219]
	s_nop 1
	v_mfma_f32_16x16x32_bf16 v[48:51], v[220:223], v[80:83], v[48:51]
	v_mfma_f32_16x16x32_bf16 v[48:51], v[224:227], v[76:79], v[48:51]
	ds_read_b128 v[216:219], v115 offset:384
	ds_read_b128 v[220:223], v208 offset:48640
	ds_read_b128 v[224:227], v208 offset:48704
	s_waitcnt lgkmcnt(9)
	v_pk_mul_f32 v[56:57], v[56:57], v[228:229]
	v_pk_mul_f32 v[58:59], v[58:59], v[230:231]
	s_nop 1
	v_mfma_f32_16x16x32_bf16 v[56:59], v[232:235], v[80:83], v[56:59]
	v_mfma_f32_16x16x32_bf16 v[56:59], v[236:239], v[76:79], v[56:59]
	ds_read_b128 v[228:231], v115 offset:448
	ds_read_b128 v[232:235], v208 offset:50944
	ds_read_b128 v[236:239], v208 offset:51008
	s_waitcnt lgkmcnt(9)
	v_pk_mul_f32 v[60:61], v[60:61], v[84:85]
	v_pk_mul_f32 v[62:63], v[62:63], v[86:87]
	s_nop 1
	v_mfma_f32_16x16x32_bf16 v[60:63], v[88:91], v[80:83], v[60:63]
	v_mfma_f32_16x16x32_bf16 v[60:63], v[92:95], v[76:79], v[60:63]
	s_waitcnt lgkmcnt(6)
	v_pk_mul_f32 v[64:65], v[64:65], v[162:163]
	v_pk_mul_f32 v[66:67], v[66:67], v[164:165]
	s_nop 1
	v_mfma_f32_16x16x32_bf16 v[64:67], v[166:169], v[80:83], v[64:67]
	v_mfma_f32_16x16x32_bf16 v[64:67], v[170:173], v[76:79], v[64:67]
	s_waitcnt lgkmcnt(3)
	v_pk_mul_f32 v[68:69], v[68:69], v[216:217]
	v_pk_mul_f32 v[70:71], v[70:71], v[218:219]
	s_nop 1
	v_mfma_f32_16x16x32_bf16 v[68:71], v[220:223], v[80:83], v[68:71]
	v_mfma_f32_16x16x32_bf16 v[68:71], v[224:227], v[76:79], v[68:71]
	s_waitcnt lgkmcnt(0)
	s_cmp_eq_u32 s93, 36
	s_barrier
	v_pk_mul_f32 v[72:73], v[72:73], v[228:229]
	v_pk_mul_f32 v[74:75], v[74:75], v[230:231]
	s_nop 1
	v_mfma_f32_16x16x32_bf16 v[72:75], v[232:235], v[80:83], v[72:75]
	v_mfma_f32_16x16x32_bf16 v[72:75], v[236:239], v[76:79], v[72:75]
	s_cbranch_scc1 .LBB0_3086
